# G1 GEMM: first K iteration of each tile peeled with SrcC=0, accumulator zeroing v_movs removed
# baseline (speedup 1.0000x reference)
; #define PG8_STAGE(bufoff, gbase, voff) do { _Pragma("unroll") for (int _i = 0; _i < 2; ++_i) \
;         __builtin_amdgcn_global_load_lds((const unsigned*)((const char*)(gbase) + (voff)[_i]), (LAS unsigned*)(lds + (bufoff) + ldsw + _i * 8192), 16, 0, 0); } while (0)
; template <class Epi>
; DI void gemm_phase(LAS unsigned char* lds, const Gemm g, int G, int c, const Epi& E) {
;     ...
;         const bool has_next = S.next(ui + 1, nxt);
;         const char* nA = has_next ? a_tile(g, nxt.pm) : cA; const char* nB = has_next ? (const char*)g.Bt + (size_t)nxt.pn * tstepB : cB;
;         for (int t = 0; t < nt; t += 2) {
;             const bool last = (t == nt - 2);
;             const char* a1 = cA + (size_t)(t + 1) * kstep;
;             const char* a2 = last ? nA : cA + (size_t)(t + 2) * kstep; const char* b2 = last ? nB : cB + (size_t)(t + 2) * kstep;
;             const char* a3 = a2 + kstep; const char* b3 = b2 + kstep;
;             PG8_LDB(B0, 0, 0); PG8_LDB(B1, 0, 1); PG8_SCHED; PG8_LDA(At, 0, 0); PG8_STAGE(PG8_SA(1, 1), a1 + hstepA, voffA);
;             PG8_WAIT_V(8); PG8_WAIT_L(0); PG8_BAR; PG8_MMA(0, 0, At, B0); PG8_MMA(0, 1, At, B1); PG8_BAR; PG8_SCHED;
;             PG8_LDA(At, 0, 1); PG8_STAGE(PG8_SB(0, 0), b2, voffB); PG8_STAGE(PG8_SB(0, 1), b2 + hstepB, voffB); PG8_STAGE(PG8_SA(0, 0), a2, voffA);
;             PG8_WAIT_V(8); PG8_WAIT_L(0); PG8_BAR; PG8_MMA(1, 0, At, B0); PG8_MMA(1, 1, At, B1); PG8_BAR; PG8_SCHED;
;             PG8_LDB(B0, 1, 0); PG8_LDB(B1, 1, 1); PG8_SCHED; PG8_LDA(At, 1, 0); PG8_STAGE(PG8_SA(0, 1), a2 + hstepA, voffA);
;             PG8_WAIT_V(8); PG8_WAIT_L(0); PG8_BAR; PG8_MMA(0, 0, At, B0); PG8_MMA(0, 1, At, B1); PG8_BAR; PG8_SCHED;
;             PG8_LDA(At, 1, 1); PG8_STAGE(PG8_SB(1, 0), b3, voffB); PG8_STAGE(PG8_SB(1, 1), b3 + hstepB, voffB); PG8_STAGE(PG8_SA(1, 0), a3, voffA);
;             PG8_WAIT_V(8); PG8_WAIT_L(0); PG8_BAR; PG8_MMA(1, 0, At, B0); PG8_MMA(1, 1, At, B1); PG8_BAR; PG8_SCHED;
;         }
;         if (wr == 0) PG8_BAR;
;         if constexpr (!Epi::AFTER_DRAIN) E(acc, cur, wr, wc, fr, fq);
;         if (!has_next) break;
; #pragma unroll
;         for (int a = 0; a < 2; ++a)
; #pragma unroll
;             for (int b = 0; b < 2; ++b)
; #pragma unroll
;                 for (int m = 0; m < 4; ++m)
; #pragma unroll
;                     for (int n = 0; n < 2; ++n) acc[a][b][m][n] = (f32x4){0.f, 0.f, 0.f, 0.f};
.LBB0_235:
	s_ashr_i32 s47, s46, 31
	s_lshl_b64 s[22:23], s[46:47], 19
	v_readlane_b32 s6, v250, 41
	s_add_u32 s50, s6, s22
	v_readlane_b32 s6, v250, 42
	s_addc_u32 s51, s6, s23
	s_and_b64 s[22:23], s[42:43], exec
	s_cselect_b32 s9, s51, s53
	s_cselect_b32 s11, s50, s52
	s_add_u32 s0, s0, 0x40080
	s_addc_u32 s1, s1, 0
	s_add_u32 s30, s52, 0x100
	s_addc_u32 s31, s53, 0
	s_mov_b32 s38, -2
	s_add_u32 s6, s0, 0xfffc0080
	s_addc_u32 s17, s1, -1
	s_add_i32 s18, 0, 0x10000
	s_cmp_eq_u32 s38, 12
	s_cselect_b32 s53, s49, s17
	s_cselect_b32 s52, s48, s6
	s_cselect_b32 s43, s9, s31
	s_cselect_b32 s42, s11, s30
	s_add_i32 s6, 0, 0x14000
	v_add_u32_e32 v172, s18, v155
	v_add_u32_e32 v188, s6, v155
	ds_read_b128 v[130:133], v172
	ds_read_b128 v[134:137], v172 offset:1024
	ds_read_b128 v[150:153], v172 offset:2048
	ds_read_b128 v[172:175], v172 offset:3072
	ds_read_b128 v[176:179], v188
	ds_read_b128 v[180:183], v188 offset:1024
	ds_read_b128 v[184:187], v188 offset:2048
	ds_read_b128 v[188:191], v188 offset:3072
	v_lshl_add_u64 v[200:201], s[0:1], 0, v[146:147]
	s_add_i32 m0, s79, 0xc000
	ds_read_b128 v[192:195], v163
	ds_read_b128 v[196:199], v163 offset:1024
	ds_read_b128 v[218:221], v163 offset:2048
	ds_read_b128 v[222:225], v163 offset:3072
	ds_read_b128 v[226:229], v163 offset:4096
	ds_read_b128 v[230:233], v163 offset:5120
	ds_read_b128 v[234:237], v163 offset:6144
	ds_read_b128 v[238:241], v163 offset:7168
	global_load_lds_dwordx4 v[200:201], off
	v_lshl_add_u64 v[200:201], s[0:1], 0, v[148:149]
	s_add_i32 m0, s79, 0xe000
	s_nop 0
	global_load_lds_dwordx4 v[200:201], off
	s_waitcnt vmcnt(8)
	s_waitcnt lgkmcnt(0)
	s_barrier
	s_setprio 1
	s_waitcnt lgkmcnt(0)
	v_mfma_f32_16x16x32_bf16 v[126:129], v[130:133], v[192:195], 0
	v_mfma_f32_16x16x32_bf16 v[122:125], v[150:153], v[192:195], 0
	v_mfma_f32_16x16x32_bf16 v[110:113], v[130:133], v[218:221], 0
	v_mfma_f32_16x16x32_bf16 v[106:109], v[150:153], v[218:221], 0
	v_mfma_f32_16x16x32_bf16 v[94:97], v[130:133], v[226:229], 0
	v_mfma_f32_16x16x32_bf16 v[90:93], v[150:153], v[226:229], 0
	v_mfma_f32_16x16x32_bf16 v[78:81], v[130:133], v[234:237], 0
	v_mfma_f32_16x16x32_bf16 v[74:77], v[150:153], v[234:237], 0
	v_mfma_f32_16x16x32_bf16 v[126:129], v[134:137], v[196:199], v[126:129]
	v_mfma_f32_16x16x32_bf16 v[122:125], v[172:175], v[196:199], v[122:125]
	v_mfma_f32_16x16x32_bf16 v[110:113], v[134:137], v[222:225], v[110:113]
	v_mfma_f32_16x16x32_bf16 v[106:109], v[172:175], v[222:225], v[106:109]
	v_mfma_f32_16x16x32_bf16 v[94:97], v[134:137], v[230:233], v[94:97]
	v_mfma_f32_16x16x32_bf16 v[90:93], v[172:175], v[230:233], v[90:93]
	v_mfma_f32_16x16x32_bf16 v[78:81], v[134:137], v[238:241], v[78:81]
	v_mfma_f32_16x16x32_bf16 v[74:77], v[172:175], v[238:241], v[74:77]
	s_setprio 0
	s_setprio 1
	v_mfma_f32_16x16x32_bf16 v[118:121], v[176:179], v[192:195], 0
	v_mfma_f32_16x16x32_bf16 v[114:117], v[184:187], v[192:195], 0
	v_mfma_f32_16x16x32_bf16 v[102:105], v[176:179], v[218:221], 0
	v_mfma_f32_16x16x32_bf16 v[98:101], v[184:187], v[218:221], 0
	v_mfma_f32_16x16x32_bf16 v[86:89], v[176:179], v[226:229], 0
	v_mfma_f32_16x16x32_bf16 v[82:85], v[184:187], v[226:229], 0
	v_mfma_f32_16x16x32_bf16 v[70:73], v[176:179], v[234:237], 0
	v_mfma_f32_16x16x32_bf16 v[66:69], v[184:187], v[234:237], 0
	v_mfma_f32_16x16x32_bf16 v[118:121], v[180:183], v[196:199], v[118:121]
	v_mfma_f32_16x16x32_bf16 v[114:117], v[188:191], v[196:199], v[114:117]
	v_mfma_f32_16x16x32_bf16 v[102:105], v[180:183], v[222:225], v[102:105]
	v_mfma_f32_16x16x32_bf16 v[98:101], v[188:191], v[222:225], v[98:101]
	v_mfma_f32_16x16x32_bf16 v[86:89], v[180:183], v[230:233], v[86:89]
	v_mfma_f32_16x16x32_bf16 v[82:85], v[188:191], v[230:233], v[82:85]
	v_mfma_f32_16x16x32_bf16 v[70:73], v[180:183], v[238:241], v[70:73]
	v_mfma_f32_16x16x32_bf16 v[66:69], v[188:191], v[238:241], v[66:69]
	s_setprio 0
	s_barrier
	s_add_i32 s17, s18, s78
	v_lshl_add_u64 v[200:201], s[42:43], 0, v[142:143]
	s_mov_b32 m0, s17
	ds_read_b128 v[192:195], v163 offset:16384
	ds_read_b128 v[196:199], v163 offset:17408
	ds_read_b128 v[218:221], v163 offset:18432
	ds_read_b128 v[222:225], v163 offset:19456
	ds_read_b128 v[226:229], v163 offset:20480
	ds_read_b128 v[230:233], v163 offset:21504
	ds_read_b128 v[234:237], v163 offset:22528
	ds_read_b128 v[238:241], v163 offset:23552
	global_load_lds_dwordx4 v[200:201], off
	s_add_i32 m0, s17, 0x2000
	s_add_u32 s22, s42, 0x40000
	v_lshl_add_u64 v[242:243], s[42:43], 0, v[138:139]
	s_addc_u32 s23, s43, 0
	s_add_i32 s6, s6, s78
	global_load_lds_dwordx4 v[242:243], off
	v_lshl_add_u64 v[244:245], s[22:23], 0, v[142:143]
	s_mov_b32 m0, s6
	v_lshl_add_u64 v[246:247], s[52:53], 0, v[140:141]
	global_load_lds_dwordx4 v[244:245], off
	v_lshl_add_u64 v[244:245], s[22:23], 0, v[138:139]
	s_add_i32 m0, s6, 0x2000
	s_nop 0
	global_load_lds_dwordx4 v[244:245], off
	v_lshl_add_u64 v[244:245], s[52:53], 0, v[0:1]
	s_mov_b32 m0, s79
	s_nop 0
	global_load_lds_dwordx4 v[244:245], off
	s_mov_b32 m0, s82
	s_nop 0
	global_load_lds_dwordx4 v[246:247], off
	s_waitcnt vmcnt(8)
	s_waitcnt lgkmcnt(0)
	s_barrier
; #define PG8_STAGE(bufoff, gbase, voff) do { _Pragma("unroll") for (int _i = 0; _i < 2; ++_i) \
;         __builtin_amdgcn_global_load_lds((const unsigned*)((const char*)(gbase) + (voff)[_i]), (LAS unsigned*)(lds + (bufoff) + ldsw + _i * 8192), 16, 0, 0); } while (0)
; #define PG8_LDA(dst, b, h) do { _Pragma("unroll") for (int m = 0; m < 4; ++m) _Pragma("unroll") for (int k = 0; k < 2; ++k) dst[m][k] = *(const LAS bf16x8*)(lds + PG8_SA(b, h) + aoff + m * 2048 + k * 1024); } while (0)
; #define PG8_LDB(dst, b, h) do { _Pragma("unroll") for (int n = 0; n < 2; ++n) _Pragma("unroll") for (int k = 0; k < 2; ++k) dst[n][k] = *(const LAS bf16x8*)(lds + PG8_SB(b, h) + boff + n * 2048 + k * 1024); } while (0)
; #define PG8_MMA(ai, bj, At, Bt) do { __builtin_amdgcn_s_setprio(1); _Pragma("unroll") for (int m = 0; m < 4; ++m) _Pragma("unroll") for (int n = 0; n < 2; ++n) _Pragma("unroll") for (int k = 0; k < 2; ++k) \
;         acc[ai][bj][m][n] = __builtin_amdgcn_mfma_f32_16x16x32_bf16(Bt[n][k], At[m][k], acc[ai][bj][m][n], 0, 0, 0); __builtin_amdgcn_s_setprio(0); } while (0)
; #define PG8_WAIT_V(n) asm volatile("s_waitcnt vmcnt(" #n ")" ::: "memory")
; #define PG8_WAIT_L(n) asm volatile("s_waitcnt lgkmcnt(" #n ")" ::: "memory")
; #define PG8_BAR __builtin_amdgcn_s_barrier()
; #define PG8_SCHED __builtin_amdgcn_sched_barrier(0)
; template <class Epi>
; DI void gemm_phase(LAS unsigned char* lds, const Gemm g, int G, int c, const Epi& E) {
;     ...
;             PG8_WAIT_V(8); PG8_WAIT_L(0); PG8_BAR; PG8_MMA(1, 0, At, B0); PG8_MMA(1, 1, At, B1); PG8_BAR; PG8_SCHED;
;             PG8_LDB(B0, 1, 0); PG8_LDB(B1, 1, 1); PG8_SCHED; PG8_LDA(At, 1, 0); PG8_STAGE(PG8_SA(0, 1), a2 + hstepA, voffA);
;             PG8_WAIT_V(8); PG8_WAIT_L(0); PG8_BAR; PG8_MMA(0, 0, At, B0); PG8_MMA(0, 1, At, B1); PG8_BAR; PG8_SCHED;
	s_setprio 1
	s_waitcnt lgkmcnt(0)
	v_mfma_f32_16x16x32_bf16 v[62:65], v[130:133], v[192:195], 0
	v_mfma_f32_16x16x32_bf16 v[58:61], v[150:153], v[192:195], 0
	v_mfma_f32_16x16x32_bf16 v[46:49], v[130:133], v[218:221], 0
	v_mfma_f32_16x16x32_bf16 v[42:45], v[150:153], v[218:221], 0
	v_mfma_f32_16x16x32_bf16 v[30:33], v[130:133], v[226:229], 0
	v_mfma_f32_16x16x32_bf16 v[26:29], v[150:153], v[226:229], 0
	v_mfma_f32_16x16x32_bf16 v[14:17], v[130:133], v[234:237], 0
	v_mfma_f32_16x16x32_bf16 v[10:13], v[150:153], v[234:237], 0
	v_mfma_f32_16x16x32_bf16 v[62:65], v[134:137], v[196:199], v[62:65]
	v_mfma_f32_16x16x32_bf16 v[58:61], v[172:175], v[196:199], v[58:61]
	v_mfma_f32_16x16x32_bf16 v[46:49], v[134:137], v[222:225], v[46:49]
	v_mfma_f32_16x16x32_bf16 v[42:45], v[172:175], v[222:225], v[42:45]
	v_mfma_f32_16x16x32_bf16 v[30:33], v[134:137], v[230:233], v[30:33]
	v_mfma_f32_16x16x32_bf16 v[26:29], v[172:175], v[230:233], v[26:29]
	v_mfma_f32_16x16x32_bf16 v[14:17], v[134:137], v[238:241], v[14:17]
	v_mfma_f32_16x16x32_bf16 v[10:13], v[172:175], v[238:241], v[10:13]
	s_setprio 0
	s_setprio 1
	v_mfma_f32_16x16x32_bf16 v[54:57], v[176:179], v[192:195], 0
	v_mfma_f32_16x16x32_bf16 v[50:53], v[184:187], v[192:195], 0
	v_mfma_f32_16x16x32_bf16 v[38:41], v[176:179], v[218:221], 0
	v_mfma_f32_16x16x32_bf16 v[34:37], v[184:187], v[218:221], 0
	v_mfma_f32_16x16x32_bf16 v[22:25], v[176:179], v[226:229], 0
	v_mfma_f32_16x16x32_bf16 v[18:21], v[184:187], v[226:229], 0
	v_mfma_f32_16x16x32_bf16 v[6:9], v[176:179], v[234:237], 0
	v_mfma_f32_16x16x32_bf16 v[2:5], v[184:187], v[234:237], 0
	v_mfma_f32_16x16x32_bf16 v[54:57], v[180:183], v[196:199], v[54:57]
	v_mfma_f32_16x16x32_bf16 v[50:53], v[188:191], v[196:199], v[50:53]
	v_mfma_f32_16x16x32_bf16 v[38:41], v[180:183], v[222:225], v[38:41]
	v_mfma_f32_16x16x32_bf16 v[34:37], v[188:191], v[222:225], v[34:37]
	v_mfma_f32_16x16x32_bf16 v[22:25], v[180:183], v[230:233], v[22:25]
	v_mfma_f32_16x16x32_bf16 v[18:21], v[188:191], v[230:233], v[18:21]
	v_mfma_f32_16x16x32_bf16 v[6:9], v[180:183], v[238:241], v[6:9]
	v_mfma_f32_16x16x32_bf16 v[2:5], v[188:191], v[238:241], v[2:5]
	s_setprio 0
	s_barrier
	s_add_i32 s6, 0, 0x18000
	s_add_i32 s17, 0, 0x1c000
	v_add_u32_e32 v172, s6, v155
	v_add_u32_e32 v188, s17, v155
	ds_read_b128 v[130:133], v172
	ds_read_b128 v[134:137], v172 offset:1024
	ds_read_b128 v[150:153], v172 offset:2048
	ds_read_b128 v[172:175], v172 offset:3072
	ds_read_b128 v[176:179], v188
	ds_read_b128 v[180:183], v188 offset:1024
	ds_read_b128 v[184:187], v188 offset:2048
	ds_read_b128 v[188:191], v188 offset:3072
	s_add_u32 s22, s52, 0x40000
	s_addc_u32 s23, s53, 0
	s_mov_b32 m0, s83
	v_lshl_add_u64 v[248:249], s[22:23], 0, v[0:1]
	ds_read_b128 v[192:195], v163 offset:32768
	ds_read_b128 v[196:199], v163 offset:33792
	ds_read_b128 v[218:221], v163 offset:34816
	ds_read_b128 v[222:225], v163 offset:35840
	ds_read_b128 v[226:229], v163 offset:36864
	ds_read_b128 v[230:233], v163 offset:37888
	ds_read_b128 v[234:237], v163 offset:38912
	ds_read_b128 v[238:241], v163 offset:39936
	global_load_lds_dwordx4 v[248:249], off
	v_lshl_add_u64 v[248:249], s[22:23], 0, v[140:141]
	s_mov_b32 m0, s84
	s_nop 0
	global_load_lds_dwordx4 v[248:249], off
	s_waitcnt vmcnt(8)
	s_waitcnt lgkmcnt(0)
	s_barrier
	s_setprio 1
	s_waitcnt lgkmcnt(0)
	v_mfma_f32_16x16x32_bf16 v[126:129], v[130:133], v[192:195], v[126:129]
	v_mfma_f32_16x16x32_bf16 v[122:125], v[150:153], v[192:195], v[122:125]
	v_mfma_f32_16x16x32_bf16 v[110:113], v[130:133], v[218:221], v[110:113]
	v_mfma_f32_16x16x32_bf16 v[106:109], v[150:153], v[218:221], v[106:109]
	v_mfma_f32_16x16x32_bf16 v[94:97], v[130:133], v[226:229], v[94:97]
	v_mfma_f32_16x16x32_bf16 v[90:93], v[150:153], v[226:229], v[90:93]
	v_mfma_f32_16x16x32_bf16 v[78:81], v[130:133], v[234:237], v[78:81]
	v_mfma_f32_16x16x32_bf16 v[74:77], v[150:153], v[234:237], v[74:77]
	v_mfma_f32_16x16x32_bf16 v[126:129], v[134:137], v[196:199], v[126:129]
	v_mfma_f32_16x16x32_bf16 v[122:125], v[172:175], v[196:199], v[122:125]
	v_mfma_f32_16x16x32_bf16 v[110:113], v[134:137], v[222:225], v[110:113]
	v_mfma_f32_16x16x32_bf16 v[106:109], v[172:175], v[222:225], v[106:109]
	v_mfma_f32_16x16x32_bf16 v[94:97], v[134:137], v[230:233], v[94:97]
	v_mfma_f32_16x16x32_bf16 v[90:93], v[172:175], v[230:233], v[90:93]
	v_mfma_f32_16x16x32_bf16 v[78:81], v[134:137], v[238:241], v[78:81]
	v_mfma_f32_16x16x32_bf16 v[74:77], v[172:175], v[238:241], v[74:77]
	s_setprio 0
	s_setprio 1
	v_mfma_f32_16x16x32_bf16 v[118:121], v[176:179], v[192:195], v[118:121]
	v_mfma_f32_16x16x32_bf16 v[114:117], v[184:187], v[192:195], v[114:117]
	v_mfma_f32_16x16x32_bf16 v[102:105], v[176:179], v[218:221], v[102:105]
	v_mfma_f32_16x16x32_bf16 v[98:101], v[184:187], v[218:221], v[98:101]
	v_mfma_f32_16x16x32_bf16 v[86:89], v[176:179], v[226:229], v[86:89]
	v_mfma_f32_16x16x32_bf16 v[82:85], v[184:187], v[226:229], v[82:85]
	v_mfma_f32_16x16x32_bf16 v[70:73], v[176:179], v[234:237], v[70:73]
	v_mfma_f32_16x16x32_bf16 v[66:69], v[184:187], v[234:237], v[66:69]
	v_mfma_f32_16x16x32_bf16 v[118:121], v[180:183], v[196:199], v[118:121]
	v_mfma_f32_16x16x32_bf16 v[114:117], v[188:191], v[196:199], v[114:117]
	v_mfma_f32_16x16x32_bf16 v[102:105], v[180:183], v[222:225], v[102:105]
	v_mfma_f32_16x16x32_bf16 v[98:101], v[188:191], v[222:225], v[98:101]
	v_mfma_f32_16x16x32_bf16 v[86:89], v[180:183], v[230:233], v[86:89]
	v_mfma_f32_16x16x32_bf16 v[82:85], v[188:191], v[230:233], v[82:85]
	v_mfma_f32_16x16x32_bf16 v[70:73], v[180:183], v[238:241], v[70:73]
	v_mfma_f32_16x16x32_bf16 v[66:69], v[188:191], v[238:241], v[66:69]
	s_setprio 0
	s_barrier
; #define PG8_STAGE(bufoff, gbase, voff) do { _Pragma("unroll") for (int _i = 0; _i < 2; ++_i) \
;         __builtin_amdgcn_global_load_lds((const unsigned*)((const char*)(gbase) + (voff)[_i]), (LAS unsigned*)(lds + (bufoff) + ldsw + _i * 8192), 16, 0, 0); } while (0)
; #define PG8_LDA(dst, b, h) do { _Pragma("unroll") for (int m = 0; m < 4; ++m) _Pragma("unroll") for (int k = 0; k < 2; ++k) dst[m][k] = *(const LAS bf16x8*)(lds + PG8_SA(b, h) + aoff + m * 2048 + k * 1024); } while (0)
; #define PG8_MMA(ai, bj, At, Bt) do { __builtin_amdgcn_s_setprio(1); _Pragma("unroll") for (int m = 0; m < 4; ++m) _Pragma("unroll") for (int n = 0; n < 2; ++n) _Pragma("unroll") for (int k = 0; k < 2; ++k) \
;         acc[ai][bj][m][n] = __builtin_amdgcn_mfma_f32_16x16x32_bf16(Bt[n][k], At[m][k], acc[ai][bj][m][n], 0, 0, 0); __builtin_amdgcn_s_setprio(0); } while (0)
; #define PG8_WAIT_V(n) asm volatile("s_waitcnt vmcnt(" #n ")" ::: "memory")
; #define PG8_WAIT_L(n) asm volatile("s_waitcnt lgkmcnt(" #n ")" ::: "memory")
; #define PG8_BAR __builtin_amdgcn_s_barrier()
; #define PG8_SCHED __builtin_amdgcn_sched_barrier(0)
; template <class Epi>
; DI void gemm_phase(LAS unsigned char* lds, const Gemm g, int G, int c, const Epi& E) {
;     ...
;             PG8_LDA(At, 1, 1); PG8_STAGE(PG8_SB(1, 0), b3, voffB); PG8_STAGE(PG8_SB(1, 1), b3 + hstepB, voffB); PG8_STAGE(PG8_SA(1, 0), a3, voffA);
;             PG8_WAIT_V(8); PG8_WAIT_L(0); PG8_BAR; PG8_MMA(1, 0, At, B0); PG8_MMA(1, 1, At, B1); PG8_BAR; PG8_SCHED;
;         }
	s_add_i32 s6, s6, s78
	v_lshl_add_u64 v[200:201], v[200:201], 0, s[14:15]
	s_mov_b32 m0, s6
	ds_read_b128 v[192:195], v163 offset:49152
	ds_read_b128 v[196:199], v163 offset:50176
	ds_read_b128 v[218:221], v163 offset:51200
	ds_read_b128 v[222:225], v163 offset:52224
	ds_read_b128 v[226:229], v163 offset:53248
	ds_read_b128 v[230:233], v163 offset:54272
	ds_read_b128 v[234:237], v163 offset:55296
	ds_read_b128 v[238:241], v163 offset:56320
	global_load_lds_dwordx4 v[200:201], off
	s_add_i32 m0, s6, 0x2000
	s_add_u32 s22, s42, 0x40080
	v_lshl_add_u64 v[200:201], v[242:243], 0, s[14:15]
	s_addc_u32 s23, s43, 0
	s_add_i32 s6, s17, s78
	global_load_lds_dwordx4 v[200:201], off
	v_lshl_add_u64 v[200:201], s[22:23], 0, v[142:143]
	s_mov_b32 m0, s6
	s_nop 0
	global_load_lds_dwordx4 v[200:201], off
	v_lshl_add_u64 v[200:201], s[22:23], 0, v[138:139]
	s_add_i32 m0, s6, 0x2000
	s_nop 0
	global_load_lds_dwordx4 v[200:201], off
	v_lshl_add_u64 v[200:201], v[244:245], 0, s[14:15]
	s_mov_b32 m0, s85
	s_nop 0
	global_load_lds_dwordx4 v[200:201], off
	v_lshl_add_u64 v[200:201], v[246:247], 0, s[14:15]
	s_mov_b32 m0, s97
	s_nop 0
	global_load_lds_dwordx4 v[200:201], off
	s_waitcnt vmcnt(8)
	s_waitcnt lgkmcnt(0)
	s_barrier
	s_setprio 1
	s_waitcnt lgkmcnt(0)
	v_mfma_f32_16x16x32_bf16 v[62:65], v[130:133], v[192:195], v[62:65]
	v_mfma_f32_16x16x32_bf16 v[58:61], v[150:153], v[192:195], v[58:61]
	v_mfma_f32_16x16x32_bf16 v[46:49], v[130:133], v[218:221], v[46:49]
	v_mfma_f32_16x16x32_bf16 v[42:45], v[150:153], v[218:221], v[42:45]
	v_mfma_f32_16x16x32_bf16 v[30:33], v[130:133], v[226:229], v[30:33]
	v_mfma_f32_16x16x32_bf16 v[26:29], v[150:153], v[226:229], v[26:29]
	v_mfma_f32_16x16x32_bf16 v[14:17], v[130:133], v[234:237], v[14:17]
	v_mfma_f32_16x16x32_bf16 v[10:13], v[150:153], v[234:237], v[10:13]
	v_mfma_f32_16x16x32_bf16 v[62:65], v[134:137], v[196:199], v[62:65]
	v_mfma_f32_16x16x32_bf16 v[58:61], v[172:175], v[196:199], v[58:61]
	v_mfma_f32_16x16x32_bf16 v[46:49], v[134:137], v[222:225], v[46:49]
	v_mfma_f32_16x16x32_bf16 v[42:45], v[172:175], v[222:225], v[42:45]
	v_mfma_f32_16x16x32_bf16 v[30:33], v[134:137], v[230:233], v[30:33]
	v_mfma_f32_16x16x32_bf16 v[26:29], v[172:175], v[230:233], v[26:29]
	v_mfma_f32_16x16x32_bf16 v[14:17], v[134:137], v[238:241], v[14:17]
	v_mfma_f32_16x16x32_bf16 v[10:13], v[172:175], v[238:241], v[10:13]
	s_setprio 0
	s_setprio 1
	v_mfma_f32_16x16x32_bf16 v[54:57], v[176:179], v[192:195], v[54:57]
	v_mfma_f32_16x16x32_bf16 v[50:53], v[184:187], v[192:195], v[50:53]
	v_mfma_f32_16x16x32_bf16 v[38:41], v[176:179], v[218:221], v[38:41]
	v_mfma_f32_16x16x32_bf16 v[34:37], v[184:187], v[218:221], v[34:37]
	v_mfma_f32_16x16x32_bf16 v[22:25], v[176:179], v[226:229], v[22:25]
	v_mfma_f32_16x16x32_bf16 v[18:21], v[184:187], v[226:229], v[18:21]
	v_mfma_f32_16x16x32_bf16 v[6:9], v[176:179], v[234:237], v[6:9]
	v_mfma_f32_16x16x32_bf16 v[2:5], v[184:187], v[234:237], v[2:5]
	v_mfma_f32_16x16x32_bf16 v[54:57], v[180:183], v[196:199], v[54:57]
	v_mfma_f32_16x16x32_bf16 v[50:53], v[188:191], v[196:199], v[50:53]
	v_mfma_f32_16x16x32_bf16 v[38:41], v[180:183], v[222:225], v[38:41]
	v_mfma_f32_16x16x32_bf16 v[34:37], v[188:191], v[222:225], v[34:37]
	v_mfma_f32_16x16x32_bf16 v[22:25], v[180:183], v[230:233], v[22:25]
	v_mfma_f32_16x16x32_bf16 v[18:21], v[188:191], v[230:233], v[18:21]
	v_mfma_f32_16x16x32_bf16 v[6:9], v[180:183], v[238:241], v[6:9]
	v_mfma_f32_16x16x32_bf16 v[2:5], v[188:191], v[238:241], v[2:5]
	s_setprio 0
	s_barrier
	s_add_i32 s38, s38, 2
	s_add_u32 s0, s0, 0x100
	s_addc_u32 s1, s1, 0
	s_add_u32 s30, s30, 0x100
	s_addc_u32 s31, s31, 0
	s_cmp_gt_u32 s38, 13
